# all four GEMM K-loops: per-segment s_setprio flips removed, static s_setprio 1 for waves 0-3
# baseline (speedup 1.0000x reference)
.LBB0_249:
	s_ashr_i32 s23, s22, 31
	s_lshl_b64 s[2:3], s[22:23], 19
	s_add_u32 s24, s41, s2
	s_addc_u32 s25, s42, s3
	s_and_b64 s[2:3], s[18:19], exec
	s_cselect_b32 s2, s25, s9
	s_cselect_b32 s3, s24, s8
	s_ashr_i32 s21, s20, 31
	s_lshl_b64 s[26:27], s[20:21], 19
	s_add_u32 s26, s43, s26
	s_addc_u32 s27, s44, s27
	s_and_b64 s[30:31], s[18:19], exec
	s_cselect_b32 s5, s27, s29
	s_cselect_b32 s7, s26, s28
	s_add_u32 s8, s8, 0x40080
	s_addc_u32 s9, s9, 0
	s_add_u32 s21, s28, 0x100
	v_mov_b32_e32 v2, 0
	s_addc_u32 s23, s29, 0
	s_mov_b32 s34, -2
	v_mov_b32_e32 v3, v2
	v_mov_b32_e32 v4, v2
	v_mov_b32_e32 v5, v2
	v_mov_b32_e32 v6, v2
	v_mov_b32_e32 v7, v2
	v_mov_b32_e32 v8, v2
	v_mov_b32_e32 v9, v2
	s_waitcnt vmcnt(0)
	v_mov_b32_e32 v18, v2
	v_mov_b32_e32 v19, v2
	v_mov_b32_e32 v20, v2
	v_mov_b32_e32 v21, v2
	v_mov_b32_e32 v22, v2
	v_mov_b32_e32 v23, v2
	v_mov_b32_e32 v24, v2
	v_mov_b32_e32 v25, v2
	v_mov_b32_e32 v34, v2
	v_mov_b32_e32 v35, v2
	v_mov_b32_e32 v36, v2
	v_mov_b32_e32 v37, v2
	v_mov_b32_e32 v38, v2
	v_mov_b32_e32 v39, v2
	v_mov_b32_e32 v40, v2
	v_mov_b32_e32 v41, v2
	v_mov_b32_e32 v50, v2
	v_mov_b32_e32 v51, v2
	v_mov_b32_e32 v52, v2
	v_mov_b32_e32 v53, v2
	v_mov_b32_e32 v54, v2
	v_mov_b32_e32 v55, v2
	v_mov_b32_e32 v56, v2
	v_mov_b32_e32 v57, v2
	v_mov_b32_e32 v10, v2
	v_mov_b32_e32 v11, v2
	v_mov_b32_e32 v12, v2
	v_mov_b32_e32 v13, v2
	v_mov_b32_e32 v14, v2
	v_mov_b32_e32 v15, v2
	v_mov_b32_e32 v16, v2
	v_mov_b32_e32 v17, v2
	v_mov_b32_e32 v26, v2
	v_mov_b32_e32 v27, v2
	v_mov_b32_e32 v28, v2
	v_mov_b32_e32 v29, v2
	v_mov_b32_e32 v30, v2
	v_mov_b32_e32 v31, v2
	v_mov_b32_e32 v32, v2
	v_mov_b32_e32 v33, v2
	v_mov_b32_e32 v42, v2
	v_mov_b32_e32 v43, v2
	v_mov_b32_e32 v44, v2
	v_mov_b32_e32 v45, v2
	v_mov_b32_e32 v46, v2
	v_mov_b32_e32 v47, v2
	v_mov_b32_e32 v48, v2
	v_mov_b32_e32 v49, v2
	v_mov_b32_e32 v58, v2
	v_mov_b32_e32 v59, v2
	v_mov_b32_e32 v60, v2
	v_mov_b32_e32 v61, v2
	v_mov_b32_e32 v62, v2
	v_mov_b32_e32 v63, v2
	v_mov_b32_e32 v64, v2
	v_mov_b32_e32 v65, v2
	v_mov_b32_e32 v66, v2
	v_mov_b32_e32 v67, v2
	v_mov_b32_e32 v68, v2
	v_mov_b32_e32 v69, v2
	v_mov_b32_e32 v70, v2
	v_mov_b32_e32 v71, v2
	v_mov_b32_e32 v72, v2
	v_mov_b32_e32 v73, v2
	v_mov_b32_e32 v82, v2
	v_mov_b32_e32 v83, v2
	v_mov_b32_e32 v84, v2
	v_mov_b32_e32 v85, v2
	v_mov_b32_e32 v86, v2
	v_mov_b32_e32 v87, v2
	v_mov_b32_e32 v88, v2
	v_mov_b32_e32 v89, v2
	v_mov_b32_e32 v98, v2
	v_mov_b32_e32 v99, v2
	v_mov_b32_e32 v100, v2
	v_mov_b32_e32 v101, v2
	v_mov_b32_e32 v102, v2
	v_mov_b32_e32 v103, v2
	v_mov_b32_e32 v104, v2
	v_mov_b32_e32 v105, v2
	v_mov_b32_e32 v114, v2
	v_mov_b32_e32 v115, v2
	v_mov_b32_e32 v116, v2
	v_mov_b32_e32 v117, v2
	v_mov_b32_e32 v118, v2
	v_mov_b32_e32 v119, v2
	v_mov_b32_e32 v120, v2
	v_mov_b32_e32 v121, v2
	v_mov_b32_e32 v74, v2
	v_mov_b32_e32 v75, v2
	v_mov_b32_e32 v76, v2
	v_mov_b32_e32 v77, v2
	v_mov_b32_e32 v78, v2
	v_mov_b32_e32 v79, v2
	v_mov_b32_e32 v80, v2
	v_mov_b32_e32 v81, v2
	v_mov_b32_e32 v90, v2
	v_mov_b32_e32 v91, v2
	v_mov_b32_e32 v92, v2
	v_mov_b32_e32 v93, v2
	v_mov_b32_e32 v94, v2
	v_mov_b32_e32 v95, v2
	v_mov_b32_e32 v96, v2
	v_mov_b32_e32 v97, v2
	v_mov_b32_e32 v106, v2
	v_mov_b32_e32 v107, v2
	v_mov_b32_e32 v108, v2
	v_mov_b32_e32 v109, v2
	v_mov_b32_e32 v110, v2
	v_mov_b32_e32 v111, v2
	v_mov_b32_e32 v112, v2
	v_mov_b32_e32 v113, v2
	v_mov_b32_e32 v122, v2
	v_mov_b32_e32 v123, v2
	v_mov_b32_e32 v124, v2
	v_mov_b32_e32 v125, v2
	v_mov_b32_e32 v126, v2
	v_mov_b32_e32 v127, v2
	v_mov_b32_e32 v128, v2
	v_mov_b32_e32 v129, v2
	s_cmp_ge_u32 s46, 0x1000
	s_cbranch_scc1 .Lmy_prio_p0
	s_setprio 1
.Lmy_prio_p0:
.LBB0_250:
	ds_read_b128 v[140:143], v170
	ds_read_b128 v[144:147], v170 offset:1024
	ds_read_b128 v[148:151], v170 offset:2048
	ds_read_b128 v[152:155], v170 offset:3072
	ds_read_b128 v[156:159], v171
	ds_read_b128 v[160:163], v171 offset:1024
	ds_read_b128 v[164:167], v171 offset:2048
	ds_read_b128 v[174:177], v171 offset:3072
	s_add_u32 s28, s8, 0xfffc0080
	s_addc_u32 s29, s9, -1
	s_cmp_eq_u32 s34, 12
	s_cselect_b32 s31, s2, s29
	s_cselect_b32 s30, s3, s28
	s_cselect_b32 s29, s5, s23
	s_cselect_b32 s28, s7, s21
	v_lshl_add_u64 v[210:211], s[8:9], 0, v[136:137]
	s_add_i32 m0, s46, 0xc000
	ds_read_b128 v[178:181], v172
	ds_read_b128 v[182:185], v172 offset:1024
	ds_read_b128 v[186:189], v172 offset:2048
	ds_read_b128 v[190:193], v172 offset:3072
	ds_read_b128 v[194:197], v172 offset:4096
	ds_read_b128 v[198:201], v172 offset:5120
	ds_read_b128 v[202:205], v172 offset:6144
	ds_read_b128 v[206:209], v172 offset:7168
	global_load_lds_dwordx4 v[210:211], off
	v_lshl_add_u64 v[210:211], s[8:9], 0, v[138:139]
	s_add_i32 m0, s46, 0xe000
	s_nop 0
	global_load_lds_dwordx4 v[210:211], off
	s_waitcnt vmcnt(8)
	s_waitcnt lgkmcnt(0)
	s_barrier
	s_waitcnt lgkmcnt(0)
	v_mfma_f32_16x16x32_bf16 v[126:129], v[140:143], v[178:181], v[126:129]
	v_mfma_f32_16x16x32_bf16 v[122:125], v[148:151], v[178:181], v[122:125]
	v_mfma_f32_16x16x32_bf16 v[110:113], v[140:143], v[186:189], v[110:113]
	v_mfma_f32_16x16x32_bf16 v[106:109], v[148:151], v[186:189], v[106:109]
	v_mfma_f32_16x16x32_bf16 v[94:97], v[140:143], v[194:197], v[94:97]
	v_mfma_f32_16x16x32_bf16 v[90:93], v[148:151], v[194:197], v[90:93]
	v_mfma_f32_16x16x32_bf16 v[78:81], v[140:143], v[202:205], v[78:81]
	v_mfma_f32_16x16x32_bf16 v[74:77], v[148:151], v[202:205], v[74:77]
	v_mfma_f32_16x16x32_bf16 v[126:129], v[144:147], v[182:185], v[126:129]
	v_mfma_f32_16x16x32_bf16 v[122:125], v[152:155], v[182:185], v[122:125]
	v_mfma_f32_16x16x32_bf16 v[110:113], v[144:147], v[190:193], v[110:113]
	v_mfma_f32_16x16x32_bf16 v[106:109], v[152:155], v[190:193], v[106:109]
	v_mfma_f32_16x16x32_bf16 v[94:97], v[144:147], v[198:201], v[94:97]
	v_mfma_f32_16x16x32_bf16 v[90:93], v[152:155], v[198:201], v[90:93]
	v_mfma_f32_16x16x32_bf16 v[78:81], v[144:147], v[206:209], v[78:81]
	v_mfma_f32_16x16x32_bf16 v[74:77], v[152:155], v[206:209], v[74:77]
	v_mfma_f32_16x16x32_bf16 v[118:121], v[156:159], v[178:181], v[118:121]
	v_mfma_f32_16x16x32_bf16 v[114:117], v[164:167], v[178:181], v[114:117]
	v_mfma_f32_16x16x32_bf16 v[102:105], v[156:159], v[186:189], v[102:105]
	v_mfma_f32_16x16x32_bf16 v[98:101], v[164:167], v[186:189], v[98:101]
	v_mfma_f32_16x16x32_bf16 v[86:89], v[156:159], v[194:197], v[86:89]
	v_mfma_f32_16x16x32_bf16 v[82:85], v[164:167], v[194:197], v[82:85]
	v_mfma_f32_16x16x32_bf16 v[70:73], v[156:159], v[202:205], v[70:73]
	v_mfma_f32_16x16x32_bf16 v[66:69], v[164:167], v[202:205], v[66:69]
	v_mfma_f32_16x16x32_bf16 v[118:121], v[160:163], v[182:185], v[118:121]
	v_mfma_f32_16x16x32_bf16 v[114:117], v[174:177], v[182:185], v[114:117]
	v_mfma_f32_16x16x32_bf16 v[102:105], v[160:163], v[190:193], v[102:105]
	v_mfma_f32_16x16x32_bf16 v[98:101], v[174:177], v[190:193], v[98:101]
	v_mfma_f32_16x16x32_bf16 v[86:89], v[160:163], v[198:201], v[86:89]
	v_mfma_f32_16x16x32_bf16 v[82:85], v[174:177], v[198:201], v[82:85]
	v_mfma_f32_16x16x32_bf16 v[70:73], v[160:163], v[206:209], v[70:73]
	v_mfma_f32_16x16x32_bf16 v[66:69], v[174:177], v[206:209], v[66:69]
	s_barrier
	s_add_i32 s35, s64, s45
	v_lshl_add_u64 v[210:211], s[28:29], 0, v[130:131]
	s_mov_b32 m0, s35
	ds_read_b128 v[178:181], v172 offset:16384
	ds_read_b128 v[182:185], v172 offset:17408
	ds_read_b128 v[186:189], v172 offset:18432
	ds_read_b128 v[190:193], v172 offset:19456
	ds_read_b128 v[194:197], v172 offset:20480
	ds_read_b128 v[198:201], v172 offset:21504
	ds_read_b128 v[202:205], v172 offset:22528
	ds_read_b128 v[206:209], v172 offset:23552
	global_load_lds_dwordx4 v[210:211], off
	s_add_i32 m0, s35, 0x2000
	s_add_u32 s36, s28, 0x40000
	v_lshl_add_u64 v[212:213], s[28:29], 0, v[132:133]
	s_addc_u32 s37, s29, 0
	s_add_i32 s35, s65, s45
	global_load_lds_dwordx4 v[212:213], off
	v_lshl_add_u64 v[214:215], s[36:37], 0, v[130:131]
	s_mov_b32 m0, s35
	v_lshl_add_u64 v[216:217], s[30:31], 0, v[132:133]
	global_load_lds_dwordx4 v[214:215], off
	v_lshl_add_u64 v[214:215], s[36:37], 0, v[132:133]
	s_add_i32 m0, s35, 0x2000
	s_nop 0
	global_load_lds_dwordx4 v[214:215], off
	v_lshl_add_u64 v[214:215], s[30:31], 0, v[130:131]
	s_mov_b32 m0, s46
	s_nop 0
	global_load_lds_dwordx4 v[214:215], off
	s_mov_b32 m0, s47
	s_nop 0
	global_load_lds_dwordx4 v[216:217], off
	s_waitcnt vmcnt(8)
	s_waitcnt lgkmcnt(0)
	s_barrier
	s_waitcnt lgkmcnt(0)
	v_mfma_f32_16x16x32_bf16 v[62:65], v[140:143], v[178:181], v[62:65]
	v_mfma_f32_16x16x32_bf16 v[58:61], v[148:151], v[178:181], v[58:61]
	v_mfma_f32_16x16x32_bf16 v[46:49], v[140:143], v[186:189], v[46:49]
	v_mfma_f32_16x16x32_bf16 v[42:45], v[148:151], v[186:189], v[42:45]
	v_mfma_f32_16x16x32_bf16 v[30:33], v[140:143], v[194:197], v[30:33]
	v_mfma_f32_16x16x32_bf16 v[26:29], v[148:151], v[194:197], v[26:29]
	v_mfma_f32_16x16x32_bf16 v[14:17], v[140:143], v[202:205], v[14:17]
	v_mfma_f32_16x16x32_bf16 v[10:13], v[148:151], v[202:205], v[10:13]
	v_mfma_f32_16x16x32_bf16 v[62:65], v[144:147], v[182:185], v[62:65]
	v_mfma_f32_16x16x32_bf16 v[58:61], v[152:155], v[182:185], v[58:61]
	v_mfma_f32_16x16x32_bf16 v[46:49], v[144:147], v[190:193], v[46:49]
	v_mfma_f32_16x16x32_bf16 v[42:45], v[152:155], v[190:193], v[42:45]
	v_mfma_f32_16x16x32_bf16 v[30:33], v[144:147], v[198:201], v[30:33]
	v_mfma_f32_16x16x32_bf16 v[26:29], v[152:155], v[198:201], v[26:29]
	v_mfma_f32_16x16x32_bf16 v[14:17], v[144:147], v[206:209], v[14:17]
	v_mfma_f32_16x16x32_bf16 v[10:13], v[152:155], v[206:209], v[10:13]
	v_mfma_f32_16x16x32_bf16 v[54:57], v[156:159], v[178:181], v[54:57]
	v_mfma_f32_16x16x32_bf16 v[50:53], v[164:167], v[178:181], v[50:53]
	v_mfma_f32_16x16x32_bf16 v[38:41], v[156:159], v[186:189], v[38:41]
	v_mfma_f32_16x16x32_bf16 v[34:37], v[164:167], v[186:189], v[34:37]
	v_mfma_f32_16x16x32_bf16 v[22:25], v[156:159], v[194:197], v[22:25]
	v_mfma_f32_16x16x32_bf16 v[18:21], v[164:167], v[194:197], v[18:21]
	v_mfma_f32_16x16x32_bf16 v[6:9], v[156:159], v[202:205], v[6:9]
	v_mfma_f32_16x16x32_bf16 v[2:5], v[164:167], v[202:205], v[2:5]
	v_mfma_f32_16x16x32_bf16 v[54:57], v[160:163], v[182:185], v[54:57]
	v_mfma_f32_16x16x32_bf16 v[50:53], v[174:177], v[182:185], v[50:53]
	v_mfma_f32_16x16x32_bf16 v[38:41], v[160:163], v[190:193], v[38:41]
	v_mfma_f32_16x16x32_bf16 v[34:37], v[174:177], v[190:193], v[34:37]
	v_mfma_f32_16x16x32_bf16 v[22:25], v[160:163], v[198:201], v[22:25]
	v_mfma_f32_16x16x32_bf16 v[18:21], v[174:177], v[198:201], v[18:21]
	v_mfma_f32_16x16x32_bf16 v[6:9], v[160:163], v[206:209], v[6:9]
	v_mfma_f32_16x16x32_bf16 v[2:5], v[174:177], v[206:209], v[2:5]
	s_barrier
	s_add_i32 s35, 0, 0x18000
	v_add_u32_e32 v134, s35, v169
	s_add_i32 s36, 0, 0x1c000
	ds_read_b128 v[140:143], v134
	ds_read_b128 v[144:147], v134 offset:1024
	ds_read_b128 v[148:151], v134 offset:2048
	ds_read_b128 v[152:155], v134 offset:3072
	v_add_u32_e32 v134, s36, v169
	ds_read_b128 v[156:159], v134
	ds_read_b128 v[160:163], v134 offset:1024
	ds_read_b128 v[164:167], v134 offset:2048
	ds_read_b128 v[174:177], v134 offset:3072
	s_add_u32 s30, s30, 0x40000
	s_addc_u32 s31, s31, 0
	s_mov_b32 m0, s48
	v_lshl_add_u64 v[218:219], s[30:31], 0, v[130:131]
	ds_read_b128 v[178:181], v172 offset:32768
	ds_read_b128 v[182:185], v172 offset:33792
	ds_read_b128 v[186:189], v172 offset:34816
	ds_read_b128 v[190:193], v172 offset:35840
	ds_read_b128 v[194:197], v172 offset:36864
	ds_read_b128 v[198:201], v172 offset:37888
	ds_read_b128 v[202:205], v172 offset:38912
	ds_read_b128 v[206:209], v172 offset:39936
	global_load_lds_dwordx4 v[218:219], off
	v_lshl_add_u64 v[218:219], s[30:31], 0, v[132:133]
	s_mov_b32 m0, s49
	s_nop 0
	global_load_lds_dwordx4 v[218:219], off
	s_waitcnt vmcnt(8)
	s_waitcnt lgkmcnt(0)
	s_barrier
	s_waitcnt lgkmcnt(0)
	v_mfma_f32_16x16x32_bf16 v[126:129], v[140:143], v[178:181], v[126:129]
	v_mfma_f32_16x16x32_bf16 v[122:125], v[148:151], v[178:181], v[122:125]
	v_mfma_f32_16x16x32_bf16 v[110:113], v[140:143], v[186:189], v[110:113]
	v_mfma_f32_16x16x32_bf16 v[106:109], v[148:151], v[186:189], v[106:109]
	v_mfma_f32_16x16x32_bf16 v[94:97], v[140:143], v[194:197], v[94:97]
	v_mfma_f32_16x16x32_bf16 v[90:93], v[148:151], v[194:197], v[90:93]
	v_mfma_f32_16x16x32_bf16 v[78:81], v[140:143], v[202:205], v[78:81]
	v_mfma_f32_16x16x32_bf16 v[74:77], v[148:151], v[202:205], v[74:77]
	v_mfma_f32_16x16x32_bf16 v[126:129], v[144:147], v[182:185], v[126:129]
	v_mfma_f32_16x16x32_bf16 v[122:125], v[152:155], v[182:185], v[122:125]
	v_mfma_f32_16x16x32_bf16 v[110:113], v[144:147], v[190:193], v[110:113]
	v_mfma_f32_16x16x32_bf16 v[106:109], v[152:155], v[190:193], v[106:109]
	v_mfma_f32_16x16x32_bf16 v[94:97], v[144:147], v[198:201], v[94:97]
	v_mfma_f32_16x16x32_bf16 v[90:93], v[152:155], v[198:201], v[90:93]
	v_mfma_f32_16x16x32_bf16 v[78:81], v[144:147], v[206:209], v[78:81]
	v_mfma_f32_16x16x32_bf16 v[74:77], v[152:155], v[206:209], v[74:77]
	v_mfma_f32_16x16x32_bf16 v[118:121], v[156:159], v[178:181], v[118:121]
	v_mfma_f32_16x16x32_bf16 v[114:117], v[164:167], v[178:181], v[114:117]
	v_mfma_f32_16x16x32_bf16 v[102:105], v[156:159], v[186:189], v[102:105]
	v_mfma_f32_16x16x32_bf16 v[98:101], v[164:167], v[186:189], v[98:101]
	v_mfma_f32_16x16x32_bf16 v[86:89], v[156:159], v[194:197], v[86:89]
	v_mfma_f32_16x16x32_bf16 v[82:85], v[164:167], v[194:197], v[82:85]
	v_mfma_f32_16x16x32_bf16 v[70:73], v[156:159], v[202:205], v[70:73]
	v_mfma_f32_16x16x32_bf16 v[66:69], v[164:167], v[202:205], v[66:69]
	v_mfma_f32_16x16x32_bf16 v[118:121], v[160:163], v[182:185], v[118:121]
	v_mfma_f32_16x16x32_bf16 v[114:117], v[174:177], v[182:185], v[114:117]
	v_mfma_f32_16x16x32_bf16 v[102:105], v[160:163], v[190:193], v[102:105]
	v_mfma_f32_16x16x32_bf16 v[98:101], v[174:177], v[190:193], v[98:101]
	v_mfma_f32_16x16x32_bf16 v[86:89], v[160:163], v[198:201], v[86:89]
	v_mfma_f32_16x16x32_bf16 v[82:85], v[174:177], v[198:201], v[82:85]
	v_mfma_f32_16x16x32_bf16 v[70:73], v[160:163], v[206:209], v[70:73]
	v_mfma_f32_16x16x32_bf16 v[66:69], v[174:177], v[206:209], v[66:69]
	s_barrier
	s_add_i32 s30, s35, s45
	v_lshl_add_u64 v[210:211], v[210:211], 0, s[14:15]
	s_mov_b32 m0, s30
	ds_read_b128 v[178:181], v172 offset:49152
	ds_read_b128 v[182:185], v172 offset:50176
	ds_read_b128 v[186:189], v172 offset:51200
	ds_read_b128 v[190:193], v172 offset:52224
	ds_read_b128 v[194:197], v172 offset:53248
	ds_read_b128 v[198:201], v172 offset:54272
	ds_read_b128 v[202:205], v172 offset:55296
	ds_read_b128 v[206:209], v172 offset:56320
	global_load_lds_dwordx4 v[210:211], off
	s_add_i32 m0, s30, 0x2000
	s_add_u32 s28, s28, 0x40080
	v_lshl_add_u64 v[210:211], v[212:213], 0, s[14:15]
	s_addc_u32 s29, s29, 0
	s_add_i32 s30, s36, s45
	global_load_lds_dwordx4 v[210:211], off
	v_lshl_add_u64 v[210:211], s[28:29], 0, v[130:131]
	s_mov_b32 m0, s30
	s_nop 0
	global_load_lds_dwordx4 v[210:211], off
	v_lshl_add_u64 v[210:211], s[28:29], 0, v[132:133]
	s_add_i32 m0, s30, 0x2000
	s_nop 0
	global_load_lds_dwordx4 v[210:211], off
	v_lshl_add_u64 v[210:211], v[214:215], 0, s[14:15]
	s_mov_b32 m0, s61
	s_nop 0
	global_load_lds_dwordx4 v[210:211], off
	v_lshl_add_u64 v[210:211], v[216:217], 0, s[14:15]
	s_mov_b32 m0, s62
	s_nop 0
	global_load_lds_dwordx4 v[210:211], off
	s_waitcnt vmcnt(8)
	s_waitcnt lgkmcnt(0)
	s_barrier
	s_waitcnt lgkmcnt(0)
	v_mfma_f32_16x16x32_bf16 v[62:65], v[140:143], v[178:181], v[62:65]
	v_mfma_f32_16x16x32_bf16 v[58:61], v[148:151], v[178:181], v[58:61]
	v_mfma_f32_16x16x32_bf16 v[46:49], v[140:143], v[186:189], v[46:49]
	v_mfma_f32_16x16x32_bf16 v[42:45], v[148:151], v[186:189], v[42:45]
	v_mfma_f32_16x16x32_bf16 v[30:33], v[140:143], v[194:197], v[30:33]
	v_mfma_f32_16x16x32_bf16 v[26:29], v[148:151], v[194:197], v[26:29]
	v_mfma_f32_16x16x32_bf16 v[14:17], v[140:143], v[202:205], v[14:17]
	v_mfma_f32_16x16x32_bf16 v[10:13], v[148:151], v[202:205], v[10:13]
	v_mfma_f32_16x16x32_bf16 v[62:65], v[144:147], v[182:185], v[62:65]
	v_mfma_f32_16x16x32_bf16 v[58:61], v[152:155], v[182:185], v[58:61]
	v_mfma_f32_16x16x32_bf16 v[46:49], v[144:147], v[190:193], v[46:49]
	v_mfma_f32_16x16x32_bf16 v[42:45], v[152:155], v[190:193], v[42:45]
	v_mfma_f32_16x16x32_bf16 v[30:33], v[144:147], v[198:201], v[30:33]
	v_mfma_f32_16x16x32_bf16 v[26:29], v[152:155], v[198:201], v[26:29]
	v_mfma_f32_16x16x32_bf16 v[14:17], v[144:147], v[206:209], v[14:17]
	v_mfma_f32_16x16x32_bf16 v[10:13], v[152:155], v[206:209], v[10:13]
	v_mfma_f32_16x16x32_bf16 v[54:57], v[156:159], v[178:181], v[54:57]
	v_mfma_f32_16x16x32_bf16 v[50:53], v[164:167], v[178:181], v[50:53]
	v_mfma_f32_16x16x32_bf16 v[38:41], v[156:159], v[186:189], v[38:41]
	v_mfma_f32_16x16x32_bf16 v[34:37], v[164:167], v[186:189], v[34:37]
	v_mfma_f32_16x16x32_bf16 v[22:25], v[156:159], v[194:197], v[22:25]
	v_mfma_f32_16x16x32_bf16 v[18:21], v[164:167], v[194:197], v[18:21]
	v_mfma_f32_16x16x32_bf16 v[6:9], v[156:159], v[202:205], v[6:9]
	v_mfma_f32_16x16x32_bf16 v[2:5], v[164:167], v[202:205], v[2:5]
	v_mfma_f32_16x16x32_bf16 v[54:57], v[160:163], v[182:185], v[54:57]
	v_mfma_f32_16x16x32_bf16 v[50:53], v[174:177], v[182:185], v[50:53]
	v_mfma_f32_16x16x32_bf16 v[38:41], v[160:163], v[190:193], v[38:41]
	v_mfma_f32_16x16x32_bf16 v[34:37], v[174:177], v[190:193], v[34:37]
	v_mfma_f32_16x16x32_bf16 v[22:25], v[160:163], v[198:201], v[22:25]
	v_mfma_f32_16x16x32_bf16 v[18:21], v[174:177], v[198:201], v[18:21]
	v_mfma_f32_16x16x32_bf16 v[6:9], v[160:163], v[206:209], v[6:9]
	v_mfma_f32_16x16x32_bf16 v[2:5], v[174:177], v[206:209], v[2:5]
	s_barrier
	s_add_i32 s34, s34, 2
	s_add_u32 s8, s8, 0x100
	s_addc_u32 s9, s9, 0
	s_add_u32 s21, s21, 0x100
	s_addc_u32 s23, s23, 0
	s_cmp_gt_u32 s34, 13
	s_cbranch_scc0 .LBB0_250
	s_setprio 0
	s_and_b64 vcc, exec, s[16:17]
	s_cbranch_vccz .LBB0_253
	s_barrier

.LBB0_430:
	s_add_u32 s66, s48, 0x100
	s_addc_u32 s67, s49, 0
	s_add_u32 s42, s22, 0x60080
	s_addc_u32 s43, s23, 0
	v_lshl_add_u64 v[138:139], s[42:43], 0, v[134:135]
	v_lshl_add_u64 v[140:141], s[42:43], 0, v[136:137]
	s_mov_b32 s68, -2
	s_mov_b64 s[42:43], 0
	s_cmp_ge_u32 s56, 0x1000
	s_cbranch_scc1 .Lmy_prio_fin
	s_setprio 1
.Lmy_prio_fin:
.LBB0_431:
	s_add_u32 s48, s22, s42
	s_addc_u32 s49, s23, s43
	s_add_u32 s48, s48, 0x100
	s_addc_u32 s49, s49, 0
	s_add_u32 s69, s66, s42
	s_addc_u32 s70, s67, s43
	s_add_i32 s71, 0, 0x10000
	s_cmpk_eq_i32 s42, 0xb00
	s_cselect_b32 s51, s35, s49
	s_cselect_b32 s50, s34, s48
	s_cselect_b32 s49, s31, s70
	s_cselect_b32 s48, s30, s69
	s_add_i32 s69, 0, 0x14000
	v_add_u32_e32 v156, s71, v142
	v_add_u32_e32 v172, s69, v142
	ds_read_b128 v[144:147], v156
	ds_read_b128 v[148:151], v156 offset:1024
	ds_read_b128 v[152:155], v156 offset:2048
	ds_read_b128 v[156:159], v156 offset:3072
	ds_read_b128 v[160:163], v172
	ds_read_b128 v[164:167], v172 offset:1024
	ds_read_b128 v[168:171], v172 offset:2048
	ds_read_b128 v[172:175], v172 offset:3072
	v_lshl_add_u64 v[210:211], v[138:139], 0, s[42:43]
	s_add_i32 m0, s56, 0xc000
	ds_read_b128 v[176:179], v143
	ds_read_b128 v[180:183], v143 offset:1024
	ds_read_b128 v[184:187], v143 offset:2048
	ds_read_b128 v[188:191], v143 offset:3072
	ds_read_b128 v[198:201], v143 offset:4096
	ds_read_b128 v[202:205], v143 offset:5120
	ds_read_b128 v[206:209], v143 offset:6144
	ds_read_b128 v[214:217], v143 offset:7168
	global_load_lds_dwordx4 v[210:211], off
	v_lshl_add_u64 v[210:211], v[140:141], 0, s[42:43]
	s_add_i32 m0, s56, 0xe000
	s_nop 0
	global_load_lds_dwordx4 v[210:211], off
	s_waitcnt vmcnt(8)
	s_waitcnt lgkmcnt(0)
	s_barrier
	s_waitcnt lgkmcnt(0)
	v_mfma_f32_16x16x32_bf16 v[128:131], v[144:147], v[176:179], v[128:131]
	v_mfma_f32_16x16x32_bf16 v[124:127], v[152:155], v[176:179], v[124:127]
	v_mfma_f32_16x16x32_bf16 v[112:115], v[144:147], v[184:187], v[112:115]
	v_mfma_f32_16x16x32_bf16 v[108:111], v[152:155], v[184:187], v[108:111]
	v_mfma_f32_16x16x32_bf16 v[100:103], v[144:147], v[198:201], v[100:103]
	v_mfma_f32_16x16x32_bf16 v[92:95], v[152:155], v[198:201], v[92:95]
	v_mfma_f32_16x16x32_bf16 v[84:87], v[144:147], v[206:209], v[84:87]
	v_mfma_f32_16x16x32_bf16 v[76:79], v[152:155], v[206:209], v[76:79]
	v_mfma_f32_16x16x32_bf16 v[128:131], v[148:151], v[180:183], v[128:131]
	v_mfma_f32_16x16x32_bf16 v[124:127], v[156:159], v[180:183], v[124:127]
	v_mfma_f32_16x16x32_bf16 v[112:115], v[148:151], v[188:191], v[112:115]
	v_mfma_f32_16x16x32_bf16 v[108:111], v[156:159], v[188:191], v[108:111]
	v_mfma_f32_16x16x32_bf16 v[100:103], v[148:151], v[202:205], v[100:103]
	v_mfma_f32_16x16x32_bf16 v[92:95], v[156:159], v[202:205], v[92:95]
	v_mfma_f32_16x16x32_bf16 v[84:87], v[148:151], v[214:217], v[84:87]
	v_mfma_f32_16x16x32_bf16 v[76:79], v[156:159], v[214:217], v[76:79]
	v_mfma_f32_16x16x32_bf16 v[120:123], v[160:163], v[176:179], v[120:123]
	v_mfma_f32_16x16x32_bf16 v[116:119], v[168:171], v[176:179], v[116:119]
	v_mfma_f32_16x16x32_bf16 v[104:107], v[160:163], v[184:187], v[104:107]
	v_mfma_f32_16x16x32_bf16 v[96:99], v[168:171], v[184:187], v[96:99]
	v_mfma_f32_16x16x32_bf16 v[88:91], v[160:163], v[198:201], v[88:91]
	v_mfma_f32_16x16x32_bf16 v[80:83], v[168:171], v[198:201], v[80:83]
	v_mfma_f32_16x16x32_bf16 v[72:75], v[160:163], v[206:209], v[72:75]
	v_mfma_f32_16x16x32_bf16 v[68:71], v[168:171], v[206:209], v[68:71]
	v_mfma_f32_16x16x32_bf16 v[120:123], v[164:167], v[180:183], v[120:123]
	v_mfma_f32_16x16x32_bf16 v[116:119], v[172:175], v[180:183], v[116:119]
	v_mfma_f32_16x16x32_bf16 v[104:107], v[164:167], v[188:191], v[104:107]
	v_mfma_f32_16x16x32_bf16 v[96:99], v[172:175], v[188:191], v[96:99]
	v_mfma_f32_16x16x32_bf16 v[88:91], v[164:167], v[202:205], v[88:91]
	v_mfma_f32_16x16x32_bf16 v[80:83], v[172:175], v[202:205], v[80:83]
	v_mfma_f32_16x16x32_bf16 v[72:75], v[164:167], v[214:217], v[72:75]
	v_mfma_f32_16x16x32_bf16 v[68:71], v[172:175], v[214:217], v[68:71]
	s_barrier
	s_add_i32 s70, s71, s55
	v_lshl_add_u64 v[210:211], s[48:49], 0, v[2:3]
	s_mov_b32 m0, s70
	ds_read_b128 v[176:179], v143 offset:16384
	ds_read_b128 v[180:183], v143 offset:17408
	ds_read_b128 v[184:187], v143 offset:18432
	ds_read_b128 v[188:191], v143 offset:19456
	ds_read_b128 v[198:201], v143 offset:20480
	ds_read_b128 v[202:205], v143 offset:21504
	ds_read_b128 v[206:209], v143 offset:22528
	ds_read_b128 v[214:217], v143 offset:23552
	global_load_lds_dwordx4 v[210:211], off
	s_add_i32 m0, s70, 0x2000
	s_add_u32 s70, s48, 0x60000
	v_lshl_add_u64 v[218:219], s[48:49], 0, v[132:133]
	s_addc_u32 s71, s49, 0
	s_add_i32 s69, s69, s55
	global_load_lds_dwordx4 v[218:219], off
	v_lshl_add_u64 v[220:221], s[70:71], 0, v[2:3]
	s_mov_b32 m0, s69
	v_lshl_add_u64 v[222:223], s[50:51], 0, v[132:133]
	global_load_lds_dwordx4 v[220:221], off
	v_lshl_add_u64 v[220:221], s[70:71], 0, v[132:133]
	s_add_i32 m0, s69, 0x2000
	s_nop 0
	global_load_lds_dwordx4 v[220:221], off
	v_lshl_add_u64 v[220:221], s[50:51], 0, v[2:3]
	s_mov_b32 m0, s56
	s_nop 0
	global_load_lds_dwordx4 v[220:221], off
	s_mov_b32 m0, s57
	s_nop 0
	global_load_lds_dwordx4 v[222:223], off
	s_waitcnt vmcnt(8)
	s_waitcnt lgkmcnt(0)
	s_barrier
	s_waitcnt lgkmcnt(0)
	v_mfma_f32_16x16x32_bf16 v[64:67], v[144:147], v[176:179], v[64:67]
	v_mfma_f32_16x16x32_bf16 v[60:63], v[152:155], v[176:179], v[60:63]
	v_mfma_f32_16x16x32_bf16 v[52:55], v[144:147], v[184:187], v[52:55]
	v_mfma_f32_16x16x32_bf16 v[44:47], v[152:155], v[184:187], v[44:47]
	v_mfma_f32_16x16x32_bf16 v[36:39], v[144:147], v[198:201], v[36:39]
	v_mfma_f32_16x16x32_bf16 v[28:31], v[152:155], v[198:201], v[28:31]
	v_mfma_f32_16x16x32_bf16 v[20:23], v[144:147], v[206:209], v[20:23]
	v_mfma_f32_16x16x32_bf16 v[12:15], v[152:155], v[206:209], v[12:15]
	v_mfma_f32_16x16x32_bf16 v[64:67], v[148:151], v[180:183], v[64:67]
	v_mfma_f32_16x16x32_bf16 v[60:63], v[156:159], v[180:183], v[60:63]
	v_mfma_f32_16x16x32_bf16 v[52:55], v[148:151], v[188:191], v[52:55]
	v_mfma_f32_16x16x32_bf16 v[44:47], v[156:159], v[188:191], v[44:47]
	v_mfma_f32_16x16x32_bf16 v[36:39], v[148:151], v[202:205], v[36:39]
	v_mfma_f32_16x16x32_bf16 v[28:31], v[156:159], v[202:205], v[28:31]
	v_mfma_f32_16x16x32_bf16 v[20:23], v[148:151], v[214:217], v[20:23]
	v_mfma_f32_16x16x32_bf16 v[12:15], v[156:159], v[214:217], v[12:15]
	v_mfma_f32_16x16x32_bf16 v[56:59], v[160:163], v[176:179], v[56:59]
	v_mfma_f32_16x16x32_bf16 v[48:51], v[168:171], v[176:179], v[48:51]
	v_mfma_f32_16x16x32_bf16 v[40:43], v[160:163], v[184:187], v[40:43]
	v_mfma_f32_16x16x32_bf16 v[32:35], v[168:171], v[184:187], v[32:35]
	v_mfma_f32_16x16x32_bf16 v[24:27], v[160:163], v[198:201], v[24:27]
	v_mfma_f32_16x16x32_bf16 v[16:19], v[168:171], v[198:201], v[16:19]
	v_mfma_f32_16x16x32_bf16 v[8:11], v[160:163], v[206:209], v[8:11]
	v_mfma_f32_16x16x32_bf16 v[4:7], v[168:171], v[206:209], v[4:7]
	v_mfma_f32_16x16x32_bf16 v[56:59], v[164:167], v[180:183], v[56:59]
	v_mfma_f32_16x16x32_bf16 v[48:51], v[172:175], v[180:183], v[48:51]
	v_mfma_f32_16x16x32_bf16 v[40:43], v[164:167], v[188:191], v[40:43]
	v_mfma_f32_16x16x32_bf16 v[32:35], v[172:175], v[188:191], v[32:35]
	v_mfma_f32_16x16x32_bf16 v[24:27], v[164:167], v[202:205], v[24:27]
	v_mfma_f32_16x16x32_bf16 v[16:19], v[172:175], v[202:205], v[16:19]
	v_mfma_f32_16x16x32_bf16 v[8:11], v[164:167], v[214:217], v[8:11]
	v_mfma_f32_16x16x32_bf16 v[4:7], v[172:175], v[214:217], v[4:7]
	s_barrier
	s_add_i32 s69, 0, 0x18000
	s_add_i32 s70, 0, 0x1c000
	v_add_u32_e32 v156, s69, v142
	v_add_u32_e32 v172, s70, v142
	ds_read_b128 v[144:147], v156
	ds_read_b128 v[148:151], v156 offset:1024
	ds_read_b128 v[152:155], v156 offset:2048
	ds_read_b128 v[156:159], v156 offset:3072
	ds_read_b128 v[160:163], v172
	ds_read_b128 v[164:167], v172 offset:1024
	ds_read_b128 v[168:171], v172 offset:2048
	ds_read_b128 v[172:175], v172 offset:3072
	s_add_u32 s50, s50, 0x60000
	s_addc_u32 s51, s51, 0
	s_mov_b32 m0, s58
	v_lshl_add_u64 v[224:225], s[50:51], 0, v[2:3]
	ds_read_b128 v[176:179], v143 offset:32768
	ds_read_b128 v[180:183], v143 offset:33792
	ds_read_b128 v[184:187], v143 offset:34816
	ds_read_b128 v[188:191], v143 offset:35840
	ds_read_b128 v[198:201], v143 offset:36864
	ds_read_b128 v[202:205], v143 offset:37888
	ds_read_b128 v[206:209], v143 offset:38912
	ds_read_b128 v[214:217], v143 offset:39936
	global_load_lds_dwordx4 v[224:225], off
	v_lshl_add_u64 v[224:225], s[50:51], 0, v[132:133]
	s_mov_b32 m0, s59
	s_nop 0
	global_load_lds_dwordx4 v[224:225], off
	s_waitcnt vmcnt(8)
	s_waitcnt lgkmcnt(0)
	s_barrier
	s_waitcnt lgkmcnt(0)
	v_mfma_f32_16x16x32_bf16 v[128:131], v[144:147], v[176:179], v[128:131]
	v_mfma_f32_16x16x32_bf16 v[124:127], v[152:155], v[176:179], v[124:127]
	v_mfma_f32_16x16x32_bf16 v[112:115], v[144:147], v[184:187], v[112:115]
	v_mfma_f32_16x16x32_bf16 v[108:111], v[152:155], v[184:187], v[108:111]
	v_mfma_f32_16x16x32_bf16 v[100:103], v[144:147], v[198:201], v[100:103]
	v_mfma_f32_16x16x32_bf16 v[92:95], v[152:155], v[198:201], v[92:95]
	v_mfma_f32_16x16x32_bf16 v[84:87], v[144:147], v[206:209], v[84:87]
	v_mfma_f32_16x16x32_bf16 v[76:79], v[152:155], v[206:209], v[76:79]
	v_mfma_f32_16x16x32_bf16 v[128:131], v[148:151], v[180:183], v[128:131]
	v_mfma_f32_16x16x32_bf16 v[124:127], v[156:159], v[180:183], v[124:127]
	v_mfma_f32_16x16x32_bf16 v[112:115], v[148:151], v[188:191], v[112:115]
	v_mfma_f32_16x16x32_bf16 v[108:111], v[156:159], v[188:191], v[108:111]
	v_mfma_f32_16x16x32_bf16 v[100:103], v[148:151], v[202:205], v[100:103]
	v_mfma_f32_16x16x32_bf16 v[92:95], v[156:159], v[202:205], v[92:95]
	v_mfma_f32_16x16x32_bf16 v[84:87], v[148:151], v[214:217], v[84:87]
	v_mfma_f32_16x16x32_bf16 v[76:79], v[156:159], v[214:217], v[76:79]
	v_mfma_f32_16x16x32_bf16 v[120:123], v[160:163], v[176:179], v[120:123]
	v_mfma_f32_16x16x32_bf16 v[116:119], v[168:171], v[176:179], v[116:119]
	v_mfma_f32_16x16x32_bf16 v[104:107], v[160:163], v[184:187], v[104:107]
	v_mfma_f32_16x16x32_bf16 v[96:99], v[168:171], v[184:187], v[96:99]
	v_mfma_f32_16x16x32_bf16 v[88:91], v[160:163], v[198:201], v[88:91]
	v_mfma_f32_16x16x32_bf16 v[80:83], v[168:171], v[198:201], v[80:83]
	v_mfma_f32_16x16x32_bf16 v[72:75], v[160:163], v[206:209], v[72:75]
	v_mfma_f32_16x16x32_bf16 v[68:71], v[168:171], v[206:209], v[68:71]
	v_mfma_f32_16x16x32_bf16 v[120:123], v[164:167], v[180:183], v[120:123]
	v_mfma_f32_16x16x32_bf16 v[116:119], v[172:175], v[180:183], v[116:119]
	v_mfma_f32_16x16x32_bf16 v[104:107], v[164:167], v[188:191], v[104:107]
	v_mfma_f32_16x16x32_bf16 v[96:99], v[172:175], v[188:191], v[96:99]
	v_mfma_f32_16x16x32_bf16 v[88:91], v[164:167], v[202:205], v[88:91]
	v_mfma_f32_16x16x32_bf16 v[80:83], v[172:175], v[202:205], v[80:83]
	v_mfma_f32_16x16x32_bf16 v[72:75], v[164:167], v[214:217], v[72:75]
	v_mfma_f32_16x16x32_bf16 v[68:71], v[172:175], v[214:217], v[68:71]
	s_barrier
	s_add_i32 s50, s69, s55
	v_lshl_add_u64 v[210:211], v[210:211], 0, s[26:27]
	s_mov_b32 m0, s50
	ds_read_b128 v[176:179], v143 offset:49152
	ds_read_b128 v[180:183], v143 offset:50176
	ds_read_b128 v[184:187], v143 offset:51200
	ds_read_b128 v[188:191], v143 offset:52224
	ds_read_b128 v[198:201], v143 offset:53248
	ds_read_b128 v[202:205], v143 offset:54272
	ds_read_b128 v[206:209], v143 offset:55296
	ds_read_b128 v[214:217], v143 offset:56320
	global_load_lds_dwordx4 v[210:211], off
	s_add_i32 m0, s50, 0x2000
	s_add_u32 s48, s48, 0x60080
	v_lshl_add_u64 v[210:211], v[218:219], 0, s[26:27]
	s_addc_u32 s49, s49, 0
	s_add_i32 s50, s70, s55
	global_load_lds_dwordx4 v[210:211], off
	v_lshl_add_u64 v[210:211], s[48:49], 0, v[2:3]
	s_mov_b32 m0, s50
	s_nop 0
	global_load_lds_dwordx4 v[210:211], off
	v_lshl_add_u64 v[210:211], s[48:49], 0, v[132:133]
	s_add_i32 m0, s50, 0x2000
	s_nop 0
	global_load_lds_dwordx4 v[210:211], off
	v_lshl_add_u64 v[210:211], v[220:221], 0, s[26:27]
	s_mov_b32 m0, s60
	s_nop 0
	global_load_lds_dwordx4 v[210:211], off
	v_lshl_add_u64 v[210:211], v[222:223], 0, s[26:27]
	s_mov_b32 m0, s61
	s_nop 0
	global_load_lds_dwordx4 v[210:211], off
	s_waitcnt vmcnt(8)
	s_waitcnt lgkmcnt(0)
	s_barrier
	s_waitcnt lgkmcnt(0)
	v_mfma_f32_16x16x32_bf16 v[64:67], v[144:147], v[176:179], v[64:67]
	v_mfma_f32_16x16x32_bf16 v[60:63], v[152:155], v[176:179], v[60:63]
	v_mfma_f32_16x16x32_bf16 v[52:55], v[144:147], v[184:187], v[52:55]
	v_mfma_f32_16x16x32_bf16 v[44:47], v[152:155], v[184:187], v[44:47]
	v_mfma_f32_16x16x32_bf16 v[36:39], v[144:147], v[198:201], v[36:39]
	v_mfma_f32_16x16x32_bf16 v[28:31], v[152:155], v[198:201], v[28:31]
	v_mfma_f32_16x16x32_bf16 v[20:23], v[144:147], v[206:209], v[20:23]
	v_mfma_f32_16x16x32_bf16 v[12:15], v[152:155], v[206:209], v[12:15]
	v_mfma_f32_16x16x32_bf16 v[64:67], v[148:151], v[180:183], v[64:67]
	v_mfma_f32_16x16x32_bf16 v[60:63], v[156:159], v[180:183], v[60:63]
	v_mfma_f32_16x16x32_bf16 v[52:55], v[148:151], v[188:191], v[52:55]
	v_mfma_f32_16x16x32_bf16 v[44:47], v[156:159], v[188:191], v[44:47]
	v_mfma_f32_16x16x32_bf16 v[36:39], v[148:151], v[202:205], v[36:39]
	v_mfma_f32_16x16x32_bf16 v[28:31], v[156:159], v[202:205], v[28:31]
	v_mfma_f32_16x16x32_bf16 v[20:23], v[148:151], v[214:217], v[20:23]
	v_mfma_f32_16x16x32_bf16 v[12:15], v[156:159], v[214:217], v[12:15]
	v_mfma_f32_16x16x32_bf16 v[56:59], v[160:163], v[176:179], v[56:59]
	v_mfma_f32_16x16x32_bf16 v[48:51], v[168:171], v[176:179], v[48:51]
	v_mfma_f32_16x16x32_bf16 v[40:43], v[160:163], v[184:187], v[40:43]
	v_mfma_f32_16x16x32_bf16 v[32:35], v[168:171], v[184:187], v[32:35]
	v_mfma_f32_16x16x32_bf16 v[24:27], v[160:163], v[198:201], v[24:27]
	v_mfma_f32_16x16x32_bf16 v[16:19], v[168:171], v[198:201], v[16:19]
	v_mfma_f32_16x16x32_bf16 v[8:11], v[160:163], v[206:209], v[8:11]
	v_mfma_f32_16x16x32_bf16 v[4:7], v[168:171], v[206:209], v[4:7]
	v_mfma_f32_16x16x32_bf16 v[56:59], v[164:167], v[180:183], v[56:59]
	v_mfma_f32_16x16x32_bf16 v[48:51], v[172:175], v[180:183], v[48:51]
	v_mfma_f32_16x16x32_bf16 v[40:43], v[164:167], v[188:191], v[40:43]
	v_mfma_f32_16x16x32_bf16 v[32:35], v[172:175], v[188:191], v[32:35]
	v_mfma_f32_16x16x32_bf16 v[24:27], v[164:167], v[202:205], v[24:27]
	v_mfma_f32_16x16x32_bf16 v[16:19], v[172:175], v[202:205], v[16:19]
	v_mfma_f32_16x16x32_bf16 v[8:11], v[164:167], v[214:217], v[8:11]
	v_mfma_f32_16x16x32_bf16 v[4:7], v[172:175], v[214:217], v[4:7]
	s_barrier
	s_add_i32 s68, s68, 2
	s_add_u32 s42, s42, 0x100
	s_addc_u32 s43, s43, 0
	s_cmp_gt_u32 s68, 21
	s_cbranch_scc0 .LBB0_431
	s_setprio 0
	s_add_u32 s42, s66, 0xffffff00
	s_addc_u32 s43, s67, -1
	s_and_b64 vcc, exec, s[40:41]
	s_cbranch_vccnz .LBB0_418
	v_mov_b32_e32 v4, 0
	s_mov_b32 s20, s63
	s_mov_b32 s53, s64
	s_mov_b64 s[22:23], s[34:35]
	s_mov_b32 s62, s65
	v_mov_b32_e32 v5, v4
	v_mov_b32_e32 v6, v4
	v_mov_b32_e32 v7, v4
	v_mov_b32_e32 v8, v4
	v_mov_b32_e32 v9, v4
	v_mov_b32_e32 v10, v4
	v_mov_b32_e32 v11, v4
	v_mov_b32_e32 v16, v4
	v_mov_b32_e32 v17, v4
	v_mov_b32_e32 v18, v4
	v_mov_b32_e32 v19, v4
	v_mov_b32_e32 v24, v4
	v_mov_b32_e32 v25, v4
	v_mov_b32_e32 v26, v4
	v_mov_b32_e32 v27, v4
	v_mov_b32_e32 v32, v4
	v_mov_b32_e32 v33, v4
	v_mov_b32_e32 v34, v4
	v_mov_b32_e32 v35, v4
	v_mov_b32_e32 v40, v4
	v_mov_b32_e32 v41, v4
	v_mov_b32_e32 v42, v4
	v_mov_b32_e32 v43, v4
	v_mov_b32_e32 v48, v4
	v_mov_b32_e32 v49, v4
	v_mov_b32_e32 v50, v4
	v_mov_b32_e32 v51, v4
	v_mov_b32_e32 v56, v4
	v_mov_b32_e32 v57, v4
	v_mov_b32_e32 v58, v4
	v_mov_b32_e32 v59, v4
	v_mov_b32_e32 v12, v4
	v_mov_b32_e32 v13, v4
	v_mov_b32_e32 v14, v4
	v_mov_b32_e32 v15, v4
	v_mov_b32_e32 v20, v4
	v_mov_b32_e32 v21, v4
	v_mov_b32_e32 v22, v4
	v_mov_b32_e32 v23, v4
	v_mov_b32_e32 v28, v4
	v_mov_b32_e32 v29, v4
	v_mov_b32_e32 v30, v4
	v_mov_b32_e32 v31, v4
	v_mov_b32_e32 v36, v4
	v_mov_b32_e32 v37, v4
	v_mov_b32_e32 v38, v4
	v_mov_b32_e32 v39, v4
	v_mov_b32_e32 v44, v4
	v_mov_b32_e32 v45, v4
	v_mov_b32_e32 v46, v4
	v_mov_b32_e32 v47, v4
	v_mov_b32_e32 v52, v4
	v_mov_b32_e32 v53, v4
	v_mov_b32_e32 v54, v4
	v_mov_b32_e32 v55, v4
	v_mov_b32_e32 v60, v4
	v_mov_b32_e32 v61, v4
	v_mov_b32_e32 v62, v4
	v_mov_b32_e32 v63, v4
	v_mov_b32_e32 v64, v4
	v_mov_b32_e32 v65, v4
	v_mov_b32_e32 v66, v4
	v_mov_b32_e32 v67, v4
	v_mov_b32_e32 v68, v4
	v_mov_b32_e32 v69, v4
	v_mov_b32_e32 v70, v4
	v_mov_b32_e32 v71, v4
	v_mov_b32_e32 v72, v4
	v_mov_b32_e32 v73, v4
	v_mov_b32_e32 v74, v4
	v_mov_b32_e32 v75, v4
	v_mov_b32_e32 v80, v4
	v_mov_b32_e32 v81, v4
	v_mov_b32_e32 v82, v4
	v_mov_b32_e32 v83, v4
	v_mov_b32_e32 v88, v4
	v_mov_b32_e32 v89, v4
	v_mov_b32_e32 v90, v4
	v_mov_b32_e32 v91, v4
	v_mov_b32_e32 v96, v4
	v_mov_b32_e32 v97, v4
	v_mov_b32_e32 v98, v4
	v_mov_b32_e32 v99, v4
	v_mov_b32_e32 v104, v4
	v_mov_b32_e32 v105, v4
	v_mov_b32_e32 v106, v4
	v_mov_b32_e32 v107, v4
	v_mov_b32_e32 v116, v4
	v_mov_b32_e32 v117, v4
	v_mov_b32_e32 v118, v4
	v_mov_b32_e32 v119, v4
	v_mov_b32_e32 v120, v4
	v_mov_b32_e32 v121, v4
	v_mov_b32_e32 v122, v4
	v_mov_b32_e32 v123, v4
	v_mov_b32_e32 v76, v4
	v_mov_b32_e32 v77, v4
	v_mov_b32_e32 v78, v4
	v_mov_b32_e32 v79, v4
	v_mov_b32_e32 v84, v4
	v_mov_b32_e32 v85, v4
	v_mov_b32_e32 v86, v4
	v_mov_b32_e32 v87, v4
	v_mov_b32_e32 v92, v4
	v_mov_b32_e32 v93, v4
	v_mov_b32_e32 v94, v4
	v_mov_b32_e32 v95, v4
	v_mov_b32_e32 v100, v4
	v_mov_b32_e32 v101, v4
	v_mov_b32_e32 v102, v4
	v_mov_b32_e32 v103, v4
	v_mov_b32_e32 v108, v4
	v_mov_b32_e32 v109, v4
	v_mov_b32_e32 v110, v4
	v_mov_b32_e32 v111, v4
	v_mov_b32_e32 v112, v4
	v_mov_b32_e32 v113, v4
	v_mov_b32_e32 v114, v4
	v_mov_b32_e32 v115, v4
	v_mov_b32_e32 v124, v4
	v_mov_b32_e32 v125, v4
	v_mov_b32_e32 v126, v4
	v_mov_b32_e32 v127, v4
	v_mov_b32_e32 v128, v4
	v_mov_b32_e32 v129, v4
	v_mov_b32_e32 v130, v4
	v_mov_b32_e32 v131, v4
	s_andn2_b64 vcc, exec, s[38:39]
	s_cbranch_vccnz .LBB0_419

.LBB0_501:
	s_add_u32 s62, s46, 0x100
	v_mov_b32_e32 v4, 0
	s_addc_u32 s63, s47, 0
	s_mov_b32 s64, -2
	s_waitcnt lgkmcnt(0)
	v_mov_b32_e32 v5, v4
	v_mov_b32_e32 v6, v4
	v_mov_b32_e32 v7, v4
	v_mov_b32_e32 v8, v4
	v_mov_b32_e32 v9, v4
	v_mov_b32_e32 v10, v4
	v_mov_b32_e32 v11, v4
	v_mov_b32_e32 v20, v4
	s_waitcnt vmcnt(0)
	v_mov_b32_e32 v21, v4
	v_mov_b32_e32 v22, v4
	v_mov_b32_e32 v23, v4
	v_mov_b32_e32 v24, v4
	v_mov_b32_e32 v25, v4
	v_mov_b32_e32 v26, v4
	v_mov_b32_e32 v27, v4
	v_mov_b32_e32 v36, v4
	v_mov_b32_e32 v37, v4
	v_mov_b32_e32 v38, v4
	v_mov_b32_e32 v39, v4
	v_mov_b32_e32 v40, v4
	v_mov_b32_e32 v41, v4
	v_mov_b32_e32 v42, v4
	v_mov_b32_e32 v43, v4
	v_mov_b32_e32 v52, v4
	v_mov_b32_e32 v53, v4
	v_mov_b32_e32 v54, v4
	v_mov_b32_e32 v55, v4
	v_mov_b32_e32 v56, v4
	v_mov_b32_e32 v57, v4
	v_mov_b32_e32 v58, v4
	v_mov_b32_e32 v59, v4
	v_mov_b32_e32 v12, v4
	v_mov_b32_e32 v13, v4
	v_mov_b32_e32 v14, v4
	v_mov_b32_e32 v15, v4
	v_mov_b32_e32 v16, v4
	v_mov_b32_e32 v17, v4
	v_mov_b32_e32 v18, v4
	v_mov_b32_e32 v19, v4
	v_mov_b32_e32 v28, v4
	v_mov_b32_e32 v29, v4
	v_mov_b32_e32 v30, v4
	v_mov_b32_e32 v31, v4
	v_mov_b32_e32 v32, v4
	v_mov_b32_e32 v33, v4
	v_mov_b32_e32 v34, v4
	v_mov_b32_e32 v35, v4
	v_mov_b32_e32 v44, v4
	v_mov_b32_e32 v45, v4
	v_mov_b32_e32 v46, v4
	v_mov_b32_e32 v47, v4
	v_mov_b32_e32 v48, v4
	v_mov_b32_e32 v49, v4
	v_mov_b32_e32 v50, v4
	v_mov_b32_e32 v51, v4
	v_mov_b32_e32 v60, v4
	v_mov_b32_e32 v61, v4
	v_mov_b32_e32 v62, v4
	v_mov_b32_e32 v63, v4
	v_mov_b32_e32 v64, v4
	v_mov_b32_e32 v65, v4
	v_mov_b32_e32 v66, v4
	v_mov_b32_e32 v67, v4
	v_mov_b32_e32 v68, v4
	v_mov_b32_e32 v69, v4
	v_mov_b32_e32 v70, v4
	v_mov_b32_e32 v71, v4
	v_mov_b32_e32 v72, v4
	v_mov_b32_e32 v73, v4
	v_mov_b32_e32 v74, v4
	v_mov_b32_e32 v75, v4
	v_mov_b32_e32 v84, v4
	v_mov_b32_e32 v85, v4
	v_mov_b32_e32 v86, v4
	v_mov_b32_e32 v87, v4
	v_mov_b32_e32 v88, v4
	v_mov_b32_e32 v89, v4
	v_mov_b32_e32 v90, v4
	v_mov_b32_e32 v91, v4
	v_mov_b32_e32 v100, v4
	v_mov_b32_e32 v101, v4
	v_mov_b32_e32 v102, v4
	v_mov_b32_e32 v103, v4
	v_mov_b32_e32 v104, v4
	v_mov_b32_e32 v105, v4
	v_mov_b32_e32 v106, v4
	v_mov_b32_e32 v107, v4
	v_mov_b32_e32 v132, v4
	v_mov_b32_e32 v133, v4
	v_mov_b32_e32 v134, v4
	v_mov_b32_e32 v135, v4
	v_mov_b32_e32 v140, v4
	v_mov_b32_e32 v141, v4
	v_mov_b32_e32 v142, v4
	v_mov_b32_e32 v143, v4
	v_mov_b32_e32 v76, v4
	v_mov_b32_e32 v77, v4
	v_mov_b32_e32 v78, v4
	v_mov_b32_e32 v79, v4
	v_mov_b32_e32 v80, v4
	v_mov_b32_e32 v81, v4
	v_mov_b32_e32 v82, v4
	v_mov_b32_e32 v83, v4
	v_mov_b32_e32 v92, v4
	v_mov_b32_e32 v93, v4
	v_mov_b32_e32 v94, v4
	v_mov_b32_e32 v95, v4
	v_mov_b32_e32 v96, v4
	v_mov_b32_e32 v97, v4
	v_mov_b32_e32 v98, v4
	v_mov_b32_e32 v99, v4
	v_mov_b32_e32 v108, v4
	v_mov_b32_e32 v109, v4
	v_mov_b32_e32 v110, v4
	v_mov_b32_e32 v111, v4
	v_mov_b32_e32 v112, v4
	v_mov_b32_e32 v113, v4
	v_mov_b32_e32 v114, v4
	v_mov_b32_e32 v115, v4
	v_mov_b32_e32 v160, v4
	v_mov_b32_e32 v161, v4
	v_mov_b32_e32 v162, v4
	v_mov_b32_e32 v163, v4
	v_mov_b32_e32 v164, v4
	v_mov_b32_e32 v165, v4
	v_mov_b32_e32 v166, v4
	v_mov_b32_e32 v167, v4
	s_cmp_ge_u32 s24, 0x1000
	s_cbranch_scc1 .Lmy_prio_out
	s_setprio 1
.Lmy_prio_out:
.LBB0_502:
	s_add_u32 s40, s44, 0x100
	s_addc_u32 s41, s45, 0
	s_add_i32 s65, 0, 0x10000
	s_cmp_eq_u32 s64, 20
	s_cselect_b32 s49, s35, s41
	s_cselect_b32 s48, s34, s40
	s_cselect_b32 s47, s43, s63
	s_cselect_b32 s46, s42, s62
	s_add_i32 s66, 0, 0x14000
	v_add_u32_e32 v128, s65, v246
	v_add_u32_e32 v152, s66, v246
	ds_read_b128 v[116:119], v128
	ds_read_b128 v[120:123], v128 offset:1024
	ds_read_b128 v[124:127], v128 offset:2048
	ds_read_b128 v[128:131], v128 offset:3072
	ds_read_b128 v[136:139], v152
	ds_read_b128 v[144:147], v152 offset:1024
	ds_read_b128 v[148:151], v152 offset:2048
	ds_read_b128 v[152:155], v152 offset:3072
	v_lshl_add_u64 v[212:213], s[44:45], 0, v[204:205]
	s_add_i32 m0, s24, 0xc000
	ds_read_b128 v[156:159], v247
	ds_read_b128 v[168:171], v247 offset:1024
	ds_read_b128 v[172:175], v247 offset:2048
	ds_read_b128 v[176:179], v247 offset:3072
	ds_read_b128 v[180:183], v247 offset:4096
	ds_read_b128 v[184:187], v247 offset:5120
	ds_read_b128 v[188:191], v247 offset:6144
	ds_read_b128 v[208:211], v247 offset:7168
	global_load_lds_dwordx4 v[212:213], off
	v_lshl_add_u64 v[212:213], s[44:45], 0, v[206:207]
	s_add_i32 m0, s24, 0xe000
	s_nop 0
	global_load_lds_dwordx4 v[212:213], off
	s_waitcnt vmcnt(8)
	s_waitcnt lgkmcnt(0)
	s_barrier
	s_waitcnt lgkmcnt(0)
	v_mfma_f32_16x16x32_bf16 v[164:167], v[116:119], v[156:159], v[164:167]
	v_mfma_f32_16x16x32_bf16 v[160:163], v[124:127], v[156:159], v[160:163]
	v_mfma_f32_16x16x32_bf16 v[112:115], v[116:119], v[172:175], v[112:115]
	v_mfma_f32_16x16x32_bf16 v[108:111], v[124:127], v[172:175], v[108:111]
	v_mfma_f32_16x16x32_bf16 v[96:99], v[116:119], v[180:183], v[96:99]
	v_mfma_f32_16x16x32_bf16 v[92:95], v[124:127], v[180:183], v[92:95]
	v_mfma_f32_16x16x32_bf16 v[80:83], v[116:119], v[188:191], v[80:83]
	v_mfma_f32_16x16x32_bf16 v[76:79], v[124:127], v[188:191], v[76:79]
	v_mfma_f32_16x16x32_bf16 v[164:167], v[120:123], v[168:171], v[164:167]
	v_mfma_f32_16x16x32_bf16 v[160:163], v[128:131], v[168:171], v[160:163]
	v_mfma_f32_16x16x32_bf16 v[112:115], v[120:123], v[176:179], v[112:115]
	v_mfma_f32_16x16x32_bf16 v[108:111], v[128:131], v[176:179], v[108:111]
	v_mfma_f32_16x16x32_bf16 v[96:99], v[120:123], v[184:187], v[96:99]
	v_mfma_f32_16x16x32_bf16 v[92:95], v[128:131], v[184:187], v[92:95]
	v_mfma_f32_16x16x32_bf16 v[80:83], v[120:123], v[208:211], v[80:83]
	v_mfma_f32_16x16x32_bf16 v[76:79], v[128:131], v[208:211], v[76:79]
	v_mfma_f32_16x16x32_bf16 v[140:143], v[136:139], v[156:159], v[140:143]
	v_mfma_f32_16x16x32_bf16 v[132:135], v[148:151], v[156:159], v[132:135]
	v_mfma_f32_16x16x32_bf16 v[104:107], v[136:139], v[172:175], v[104:107]
	v_mfma_f32_16x16x32_bf16 v[100:103], v[148:151], v[172:175], v[100:103]
	v_mfma_f32_16x16x32_bf16 v[88:91], v[136:139], v[180:183], v[88:91]
	v_mfma_f32_16x16x32_bf16 v[84:87], v[148:151], v[180:183], v[84:87]
	v_mfma_f32_16x16x32_bf16 v[72:75], v[136:139], v[188:191], v[72:75]
	v_mfma_f32_16x16x32_bf16 v[68:71], v[148:151], v[188:191], v[68:71]
	v_mfma_f32_16x16x32_bf16 v[140:143], v[144:147], v[168:171], v[140:143]
	v_mfma_f32_16x16x32_bf16 v[132:135], v[152:155], v[168:171], v[132:135]
	v_mfma_f32_16x16x32_bf16 v[104:107], v[144:147], v[176:179], v[104:107]
	v_mfma_f32_16x16x32_bf16 v[100:103], v[152:155], v[176:179], v[100:103]
	v_mfma_f32_16x16x32_bf16 v[88:91], v[144:147], v[184:187], v[88:91]
	v_mfma_f32_16x16x32_bf16 v[84:87], v[152:155], v[184:187], v[84:87]
	v_mfma_f32_16x16x32_bf16 v[72:75], v[144:147], v[208:211], v[72:75]
	v_mfma_f32_16x16x32_bf16 v[68:71], v[152:155], v[208:211], v[68:71]
	s_barrier
	s_add_i32 s44, s65, s14
	v_lshl_add_u64 v[212:213], s[46:47], 0, v[2:3]
	s_mov_b32 m0, s44
	ds_read_b128 v[156:159], v247 offset:16384
	ds_read_b128 v[168:171], v247 offset:17408
	ds_read_b128 v[172:175], v247 offset:18432
	ds_read_b128 v[176:179], v247 offset:19456
	ds_read_b128 v[180:183], v247 offset:20480
	ds_read_b128 v[184:187], v247 offset:21504
	ds_read_b128 v[188:191], v247 offset:22528
	ds_read_b128 v[208:211], v247 offset:23552
	global_load_lds_dwordx4 v[212:213], off
	s_add_i32 m0, s44, 0x2000
	s_add_u32 s44, s46, 0x60000
	v_lshl_add_u64 v[214:215], s[46:47], 0, v[202:203]
	s_addc_u32 s45, s47, 0
	s_add_i32 s65, s66, s14
	global_load_lds_dwordx4 v[214:215], off
	v_lshl_add_u64 v[216:217], s[44:45], 0, v[2:3]
	s_mov_b32 m0, s65
	v_lshl_add_u64 v[218:219], s[48:49], 0, v[200:201]
	global_load_lds_dwordx4 v[216:217], off
	v_lshl_add_u64 v[216:217], s[44:45], 0, v[202:203]
	s_add_i32 m0, s65, 0x2000
	s_nop 0
	global_load_lds_dwordx4 v[216:217], off
	v_lshl_add_u64 v[216:217], s[48:49], 0, v[198:199]
	s_mov_b32 m0, s24
	s_nop 0
	global_load_lds_dwordx4 v[216:217], off
	s_mov_b32 m0, s28
	s_nop 0
	global_load_lds_dwordx4 v[218:219], off
	s_waitcnt vmcnt(8)
	s_waitcnt lgkmcnt(0)
	s_barrier
	s_waitcnt lgkmcnt(0)
	v_mfma_f32_16x16x32_bf16 v[64:67], v[116:119], v[156:159], v[64:67]
	v_mfma_f32_16x16x32_bf16 v[60:63], v[124:127], v[156:159], v[60:63]
	v_mfma_f32_16x16x32_bf16 v[48:51], v[116:119], v[172:175], v[48:51]
	v_mfma_f32_16x16x32_bf16 v[44:47], v[124:127], v[172:175], v[44:47]
	v_mfma_f32_16x16x32_bf16 v[32:35], v[116:119], v[180:183], v[32:35]
	v_mfma_f32_16x16x32_bf16 v[28:31], v[124:127], v[180:183], v[28:31]
	v_mfma_f32_16x16x32_bf16 v[16:19], v[116:119], v[188:191], v[16:19]
	v_mfma_f32_16x16x32_bf16 v[12:15], v[124:127], v[188:191], v[12:15]
	v_mfma_f32_16x16x32_bf16 v[64:67], v[120:123], v[168:171], v[64:67]
	v_mfma_f32_16x16x32_bf16 v[60:63], v[128:131], v[168:171], v[60:63]
	v_mfma_f32_16x16x32_bf16 v[48:51], v[120:123], v[176:179], v[48:51]
	v_mfma_f32_16x16x32_bf16 v[44:47], v[128:131], v[176:179], v[44:47]
	v_mfma_f32_16x16x32_bf16 v[32:35], v[120:123], v[184:187], v[32:35]
	v_mfma_f32_16x16x32_bf16 v[28:31], v[128:131], v[184:187], v[28:31]
	v_mfma_f32_16x16x32_bf16 v[16:19], v[120:123], v[208:211], v[16:19]
	v_mfma_f32_16x16x32_bf16 v[12:15], v[128:131], v[208:211], v[12:15]
	v_mfma_f32_16x16x32_bf16 v[56:59], v[136:139], v[156:159], v[56:59]
	v_mfma_f32_16x16x32_bf16 v[52:55], v[148:151], v[156:159], v[52:55]
	v_mfma_f32_16x16x32_bf16 v[40:43], v[136:139], v[172:175], v[40:43]
	v_mfma_f32_16x16x32_bf16 v[36:39], v[148:151], v[172:175], v[36:39]
	v_mfma_f32_16x16x32_bf16 v[24:27], v[136:139], v[180:183], v[24:27]
	v_mfma_f32_16x16x32_bf16 v[20:23], v[148:151], v[180:183], v[20:23]
	v_mfma_f32_16x16x32_bf16 v[8:11], v[136:139], v[188:191], v[8:11]
	v_mfma_f32_16x16x32_bf16 v[4:7], v[148:151], v[188:191], v[4:7]
	v_mfma_f32_16x16x32_bf16 v[56:59], v[144:147], v[168:171], v[56:59]
	v_mfma_f32_16x16x32_bf16 v[52:55], v[152:155], v[168:171], v[52:55]
	v_mfma_f32_16x16x32_bf16 v[40:43], v[144:147], v[176:179], v[40:43]
	v_mfma_f32_16x16x32_bf16 v[36:39], v[152:155], v[176:179], v[36:39]
	v_mfma_f32_16x16x32_bf16 v[24:27], v[144:147], v[184:187], v[24:27]
	v_mfma_f32_16x16x32_bf16 v[20:23], v[152:155], v[184:187], v[20:23]
	v_mfma_f32_16x16x32_bf16 v[8:11], v[144:147], v[208:211], v[8:11]
	v_mfma_f32_16x16x32_bf16 v[4:7], v[152:155], v[208:211], v[4:7]
	s_barrier
	s_add_i32 s65, 0, 0x18000
	s_add_i32 s66, 0, 0x1c000
	v_add_u32_e32 v128, s65, v246
	v_add_u32_e32 v152, s66, v246
	ds_read_b128 v[116:119], v128
	ds_read_b128 v[120:123], v128 offset:1024
	ds_read_b128 v[124:127], v128 offset:2048
	ds_read_b128 v[128:131], v128 offset:3072
	ds_read_b128 v[136:139], v152
	ds_read_b128 v[144:147], v152 offset:1024
	ds_read_b128 v[148:151], v152 offset:2048
	ds_read_b128 v[152:155], v152 offset:3072
	s_add_u32 s44, s48, 0x60000
	s_addc_u32 s45, s49, 0
	s_mov_b32 m0, s29
	v_lshl_add_u64 v[220:221], s[44:45], 0, v[198:199]
	ds_read_b128 v[156:159], v247 offset:32768
	ds_read_b128 v[168:171], v247 offset:33792
	ds_read_b128 v[172:175], v247 offset:34816
	ds_read_b128 v[176:179], v247 offset:35840
	ds_read_b128 v[180:183], v247 offset:36864
	ds_read_b128 v[184:187], v247 offset:37888
	ds_read_b128 v[188:191], v247 offset:38912
	ds_read_b128 v[208:211], v247 offset:39936
	global_load_lds_dwordx4 v[220:221], off
	v_lshl_add_u64 v[220:221], s[44:45], 0, v[200:201]
	s_mov_b32 m0, s50
	s_nop 0
	global_load_lds_dwordx4 v[220:221], off
	s_waitcnt vmcnt(8)
	s_waitcnt lgkmcnt(0)
	s_barrier
	s_waitcnt lgkmcnt(0)
	v_mfma_f32_16x16x32_bf16 v[164:167], v[116:119], v[156:159], v[164:167]
	v_mfma_f32_16x16x32_bf16 v[160:163], v[124:127], v[156:159], v[160:163]
	v_mfma_f32_16x16x32_bf16 v[112:115], v[116:119], v[172:175], v[112:115]
	v_mfma_f32_16x16x32_bf16 v[108:111], v[124:127], v[172:175], v[108:111]
	v_mfma_f32_16x16x32_bf16 v[96:99], v[116:119], v[180:183], v[96:99]
	v_mfma_f32_16x16x32_bf16 v[92:95], v[124:127], v[180:183], v[92:95]
	v_mfma_f32_16x16x32_bf16 v[80:83], v[116:119], v[188:191], v[80:83]
	v_mfma_f32_16x16x32_bf16 v[76:79], v[124:127], v[188:191], v[76:79]
	v_mfma_f32_16x16x32_bf16 v[164:167], v[120:123], v[168:171], v[164:167]
	v_mfma_f32_16x16x32_bf16 v[160:163], v[128:131], v[168:171], v[160:163]
	v_mfma_f32_16x16x32_bf16 v[112:115], v[120:123], v[176:179], v[112:115]
	v_mfma_f32_16x16x32_bf16 v[108:111], v[128:131], v[176:179], v[108:111]
	v_mfma_f32_16x16x32_bf16 v[96:99], v[120:123], v[184:187], v[96:99]
	v_mfma_f32_16x16x32_bf16 v[92:95], v[128:131], v[184:187], v[92:95]
	v_mfma_f32_16x16x32_bf16 v[80:83], v[120:123], v[208:211], v[80:83]
	v_mfma_f32_16x16x32_bf16 v[76:79], v[128:131], v[208:211], v[76:79]
	v_mfma_f32_16x16x32_bf16 v[140:143], v[136:139], v[156:159], v[140:143]
	v_mfma_f32_16x16x32_bf16 v[132:135], v[148:151], v[156:159], v[132:135]
	v_mfma_f32_16x16x32_bf16 v[104:107], v[136:139], v[172:175], v[104:107]
	v_mfma_f32_16x16x32_bf16 v[100:103], v[148:151], v[172:175], v[100:103]
	v_mfma_f32_16x16x32_bf16 v[88:91], v[136:139], v[180:183], v[88:91]
	v_mfma_f32_16x16x32_bf16 v[84:87], v[148:151], v[180:183], v[84:87]
	v_mfma_f32_16x16x32_bf16 v[72:75], v[136:139], v[188:191], v[72:75]
	v_mfma_f32_16x16x32_bf16 v[68:71], v[148:151], v[188:191], v[68:71]
	v_mfma_f32_16x16x32_bf16 v[140:143], v[144:147], v[168:171], v[140:143]
	v_mfma_f32_16x16x32_bf16 v[132:135], v[152:155], v[168:171], v[132:135]
	v_mfma_f32_16x16x32_bf16 v[104:107], v[144:147], v[176:179], v[104:107]
	v_mfma_f32_16x16x32_bf16 v[100:103], v[152:155], v[176:179], v[100:103]
	v_mfma_f32_16x16x32_bf16 v[88:91], v[144:147], v[184:187], v[88:91]
	v_mfma_f32_16x16x32_bf16 v[84:87], v[152:155], v[184:187], v[84:87]
	v_mfma_f32_16x16x32_bf16 v[72:75], v[144:147], v[208:211], v[72:75]
	v_mfma_f32_16x16x32_bf16 v[68:71], v[152:155], v[208:211], v[68:71]
	s_barrier
	s_add_i32 s44, s65, s14
	v_lshl_add_u64 v[212:213], v[212:213], 0, s[26:27]
	s_mov_b32 m0, s44
	ds_read_b128 v[156:159], v247 offset:49152
	ds_read_b128 v[168:171], v247 offset:50176
	ds_read_b128 v[172:175], v247 offset:51200
	ds_read_b128 v[176:179], v247 offset:52224
	ds_read_b128 v[180:183], v247 offset:53248
	ds_read_b128 v[184:187], v247 offset:54272
	ds_read_b128 v[188:191], v247 offset:55296
	ds_read_b128 v[208:211], v247 offset:56320
	global_load_lds_dwordx4 v[212:213], off
	s_add_i32 m0, s44, 0x2000
	s_add_u32 s44, s46, 0x60080
	v_lshl_add_u64 v[212:213], v[214:215], 0, s[26:27]
	s_addc_u32 s45, s47, 0
	s_add_i32 s46, s66, s14
	global_load_lds_dwordx4 v[212:213], off
	v_lshl_add_u64 v[212:213], s[44:45], 0, v[2:3]
	s_mov_b32 m0, s46
	s_nop 0
	global_load_lds_dwordx4 v[212:213], off
	v_lshl_add_u64 v[212:213], s[44:45], 0, v[202:203]
	s_add_i32 m0, s46, 0x2000
	s_nop 0
	global_load_lds_dwordx4 v[212:213], off
	v_lshl_add_u64 v[212:213], v[216:217], 0, s[26:27]
	s_mov_b32 m0, s53
	s_nop 0
	global_load_lds_dwordx4 v[212:213], off
	v_lshl_add_u64 v[212:213], v[218:219], 0, s[26:27]
	s_mov_b32 m0, s54
	s_nop 0
	global_load_lds_dwordx4 v[212:213], off
	s_waitcnt vmcnt(8)
	s_waitcnt lgkmcnt(0)
	s_barrier
	s_waitcnt lgkmcnt(0)
	v_mfma_f32_16x16x32_bf16 v[64:67], v[116:119], v[156:159], v[64:67]
	v_mfma_f32_16x16x32_bf16 v[60:63], v[124:127], v[156:159], v[60:63]
	v_mfma_f32_16x16x32_bf16 v[48:51], v[116:119], v[172:175], v[48:51]
	v_mfma_f32_16x16x32_bf16 v[44:47], v[124:127], v[172:175], v[44:47]
	v_mfma_f32_16x16x32_bf16 v[32:35], v[116:119], v[180:183], v[32:35]
	v_mfma_f32_16x16x32_bf16 v[28:31], v[124:127], v[180:183], v[28:31]
	v_mfma_f32_16x16x32_bf16 v[16:19], v[116:119], v[188:191], v[16:19]
	v_mfma_f32_16x16x32_bf16 v[12:15], v[124:127], v[188:191], v[12:15]
	v_mfma_f32_16x16x32_bf16 v[64:67], v[120:123], v[168:171], v[64:67]
	v_mfma_f32_16x16x32_bf16 v[60:63], v[128:131], v[168:171], v[60:63]
	v_mfma_f32_16x16x32_bf16 v[48:51], v[120:123], v[176:179], v[48:51]
	v_mfma_f32_16x16x32_bf16 v[44:47], v[128:131], v[176:179], v[44:47]
	v_mfma_f32_16x16x32_bf16 v[32:35], v[120:123], v[184:187], v[32:35]
	v_mfma_f32_16x16x32_bf16 v[28:31], v[128:131], v[184:187], v[28:31]
	v_mfma_f32_16x16x32_bf16 v[16:19], v[120:123], v[208:211], v[16:19]
	v_mfma_f32_16x16x32_bf16 v[12:15], v[128:131], v[208:211], v[12:15]
	v_mfma_f32_16x16x32_bf16 v[56:59], v[136:139], v[156:159], v[56:59]
	v_mfma_f32_16x16x32_bf16 v[52:55], v[148:151], v[156:159], v[52:55]
	v_mfma_f32_16x16x32_bf16 v[40:43], v[136:139], v[172:175], v[40:43]
	v_mfma_f32_16x16x32_bf16 v[36:39], v[148:151], v[172:175], v[36:39]
	v_mfma_f32_16x16x32_bf16 v[24:27], v[136:139], v[180:183], v[24:27]
	v_mfma_f32_16x16x32_bf16 v[20:23], v[148:151], v[180:183], v[20:23]
	v_mfma_f32_16x16x32_bf16 v[8:11], v[136:139], v[188:191], v[8:11]
	v_mfma_f32_16x16x32_bf16 v[4:7], v[148:151], v[188:191], v[4:7]
	v_mfma_f32_16x16x32_bf16 v[56:59], v[144:147], v[168:171], v[56:59]
	v_mfma_f32_16x16x32_bf16 v[52:55], v[152:155], v[168:171], v[52:55]
	v_mfma_f32_16x16x32_bf16 v[40:43], v[144:147], v[176:179], v[40:43]
	v_mfma_f32_16x16x32_bf16 v[36:39], v[152:155], v[176:179], v[36:39]
	v_mfma_f32_16x16x32_bf16 v[24:27], v[144:147], v[184:187], v[24:27]
	v_mfma_f32_16x16x32_bf16 v[20:23], v[152:155], v[184:187], v[20:23]
	v_mfma_f32_16x16x32_bf16 v[8:11], v[144:147], v[208:211], v[8:11]
	v_mfma_f32_16x16x32_bf16 v[4:7], v[152:155], v[208:211], v[4:7]
	s_barrier
	s_add_i32 s64, s64, 2
	s_add_u32 s62, s62, 0x100
	s_addc_u32 s63, s63, 0
	s_cmp_gt_u32 s64, 21
	s_mov_b64 s[44:45], s[40:41]
	s_cbranch_scc0 .LBB0_502
	s_setprio 0
	s_and_b64 vcc, exec, s[30:31]
	s_cbranch_vccz .LBB0_505
	s_barrier
